# PRE S0: 8-lane sum of squares via DPP (quad_perm, row_half_mirror) instead of three serial ds_bpermute LDS round trips
# baseline (speedup 1.0000x reference)
.LBB0_81:
	v_mov_b32_e32 v1, v180
	v_mov_b32_e32 v48, v180
	v_add_lshl_u32 v240, s77, v1, 4
	s_nop 0
	v_lshlrev_b32_e32 v45, 16, v104
	v_and_b32_e32 v49, 7, v48
	v_lshlrev_b32_e32 v50, 5, v49
	v_add_u32_e32 v51, 0, v50
	v_add_u32_e32 v2, 0x25400, v51
	v_add_u32_e32 v3, 0x25600, v51
	ds_read_b128 v[28:31], v2
	ds_read_b128 v[32:35], v2 offset:16
	ds_read_b128 v[36:39], v3
	ds_read_b128 v[40:43], v3 offset:16
	v_lshlrev_b32_e32 v2, 16, v100
	v_lshlrev_b32_e32 v44, 16, v108
	v_pk_add_f32 v[44:45], v[44:45], v[2:3] op_sel_hi:[1,0] neg_lo:[0,1] neg_hi:[0,1]
	s_waitcnt lgkmcnt(3)
	global_load_dwordx4 v[20:23], v240, s[54:55]
	v_mov_b32_e32 v46, v28
	s_waitcnt lgkmcnt(1)
	v_mov_b32_e32 v47, v36
	v_pk_mul_f32 v[44:45], v[44:45], v[46:47]
	v_mov_b32_e32 v36, v29
	v_add_f32_e32 v2, v44, v2
	v_add_f32_e32 v3, v2, v45
	v_and_b32_e32 v2, 0xffff0000, v100
	v_and_b32_e32 v45, 0xffff0000, v104
	v_and_b32_e32 v44, 0xffff0000, v108
	v_pk_add_f32 v[44:45], v[44:45], v[2:3] op_sel_hi:[1,0] neg_lo:[0,1] neg_hi:[0,1]
	v_add_u32_e32 v1, s42, v48
	v_pk_mul_f32 v[28:29], v[44:45], v[36:37]
	v_mov_b32_e32 v36, v30
	v_add_f32_e32 v2, v28, v2
	v_add_f32_e32 v44, v2, v29
	v_lshlrev_b32_e32 v2, 16, v101
	v_lshlrev_b32_e32 v29, 16, v105
	v_lshlrev_b32_e32 v28, 16, v109
	v_pk_add_f32 v[28:29], v[28:29], v[2:3] op_sel_hi:[1,0] neg_lo:[0,1] neg_hi:[0,1]
	v_mov_b32_e32 v37, v38
	v_pk_mul_f32 v[28:29], v[28:29], v[36:37]
	v_mov_b32_e32 v38, v31
	v_add_f32_e32 v2, v28, v2
	v_add_f32_e32 v36, v2, v29
	v_and_b32_e32 v2, 0xffff0000, v101
	v_and_b32_e32 v29, 0xffff0000, v105
	v_and_b32_e32 v28, 0xffff0000, v109
	v_pk_add_f32 v[28:29], v[28:29], v[2:3] op_sel_hi:[1,0] neg_lo:[0,1] neg_hi:[0,1]
	v_mov_b32_e32 v30, v32
	v_pk_mul_f32 v[28:29], v[28:29], v[38:39]
	s_waitcnt lgkmcnt(0)
	v_mov_b32_e32 v31, v40
	v_add_f32_e32 v2, v28, v2
	v_add_f32_e32 v37, v2, v29
	v_lshlrev_b32_e32 v2, 16, v102
	v_lshlrev_b32_e32 v29, 16, v106
	v_lshlrev_b32_e32 v28, 16, v110
	v_pk_add_f32 v[28:29], v[28:29], v[2:3] op_sel_hi:[1,0] neg_lo:[0,1] neg_hi:[0,1]
	v_mov_b32_e32 v40, v33
	v_pk_mul_f32 v[28:29], v[28:29], v[30:31]
	v_mov_b32_e32 v30, v34
	v_add_f32_e32 v2, v28, v2
	v_add_f32_e32 v32, v2, v29
	v_and_b32_e32 v2, 0xffff0000, v102
	global_load_dwordx4 v[24:27], v240, s[58:59]
	v_and_b32_e32 v29, 0xffff0000, v106
	v_and_b32_e32 v28, 0xffff0000, v110
	v_pk_add_f32 v[28:29], v[28:29], v[2:3] op_sel_hi:[1,0] neg_lo:[0,1] neg_hi:[0,1]
	v_mov_b32_e32 v31, v42
	v_pk_mul_f32 v[28:29], v[28:29], v[40:41]
	v_mov_b32_e32 v42, v35
	v_add_f32_e32 v2, v28, v2
	v_add_f32_e32 v33, v2, v29
	v_lshlrev_b32_e32 v2, 16, v103
	v_lshlrev_b32_e32 v29, 16, v107
	v_lshlrev_b32_e32 v28, 16, v111
	v_pk_add_f32 v[28:29], v[28:29], v[2:3] op_sel_hi:[1,0] neg_lo:[0,1] neg_hi:[0,1]
	v_ashrrev_i32_e32 v1, 3, v1
	v_pk_mul_f32 v[28:29], v[28:29], v[30:31]
	v_add_f32_e32 v30, v44, v44
	v_add_f32_e32 v2, v28, v2
	v_add_f32_e32 v34, v2, v29
	v_and_b32_e32 v2, 0xffff0000, v103
	v_and_b32_e32 v29, 0xffff0000, v107
	v_and_b32_e32 v28, 0xffff0000, v111
	v_pk_add_f32 v[28:29], v[28:29], v[2:3] op_sel_hi:[1,0] neg_lo:[0,1] neg_hi:[0,1]
	v_add_f32_e32 v3, v3, v3
	v_mul_f32_e32 v3, 0x3fb8aa3b, v3
	v_exp_f32_e32 v3, v3
	v_mul_f32_e32 v30, 0x3fb8aa3b, v30
	v_exp_f32_e32 v31, v30
	v_pk_mul_f32 v[28:29], v[28:29], v[42:43]
	v_add_f32_e32 v3, 1.0, v3
	v_rcp_f32_e32 v30, v3
	v_add_f32_e32 v3, 1.0, v31
	v_rcp_f32_e32 v31, v3
	v_add_f32_e32 v2, v28, v2
	v_add_f32_e32 v28, v36, v36
	v_mul_f32_e32 v28, 0x3fb8aa3b, v28
	v_add_f32_e32 v29, v2, v29
	v_pk_fma_f32 v[2:3], v[30:31], 2.0, 1.0 op_sel_hi:[1,0,0] neg_lo:[1,0,0] neg_hi:[1,0,0]
	v_exp_f32_e32 v30, v28
	v_add_f32_e32 v28, v37, v37
	v_mul_f32_e32 v28, 0x3fb8aa3b, v28
	v_exp_f32_e32 v31, v28
	v_cvt_pk_bf16_f32 v28, v2, v3
	v_add_f32_e32 v2, 1.0, v30
	v_add_f32_e32 v30, v32, v32
	v_add_f32_e32 v3, 1.0, v31
	v_add_f32_e32 v31, v33, v33
	global_load_dwordx4 v[60:63], v240, s[54:55] offset:1024
	v_mul_f32_e32 v30, 0x3fb8aa3b, v30
	v_mul_f32_e32 v31, 0x3fb8aa3b, v31
	v_add_f32_e32 v32, v34, v34
	v_add_f32_e32 v29, v29, v29
	v_exp_f32_e32 v30, v30
	v_exp_f32_e32 v31, v31
	v_mul_f32_e32 v32, 0x3fb8aa3b, v32
	v_mul_f32_e32 v29, 0x3fb8aa3b, v29
	v_exp_f32_e32 v32, v32
	v_exp_f32_e32 v29, v29
	v_rcp_f32_e32 v2, v2
	v_rcp_f32_e32 v3, v3
	v_add_f32_e32 v30, 1.0, v30
	v_add_f32_e32 v31, 1.0, v31
	v_rcp_f32_e32 v30, v30
	v_rcp_f32_e32 v31, v31
	v_add_f32_e32 v32, 1.0, v32
	v_add_f32_e32 v29, 1.0, v29
	v_rcp_f32_e32 v32, v32
	v_rcp_f32_e32 v33, v29
	v_pk_fma_f32 v[2:3], v[2:3], 2.0, 1.0 op_sel_hi:[1,0,0] neg_lo:[1,0,0] neg_hi:[1,0,0]
	v_mul_lo_u32 v76, v1, s64
	v_cvt_pk_bf16_f32 v29, v2, v3
	v_pk_fma_f32 v[2:3], v[30:31], 2.0, 1.0 op_sel_hi:[1,0,0] neg_lo:[1,0,0] neg_hi:[1,0,0]
	v_lshlrev_b32_e32 v77, 4, v49
	v_cvt_pk_bf16_f32 v30, v2, v3
	v_pk_fma_f32 v[2:3], v[32:33], 2.0, 1.0 op_sel_hi:[1,0,0] neg_lo:[1,0,0] neg_hi:[1,0,0]
	v_readlane_b32 s27, v253, 61
	v_cvt_pk_bf16_f32 v31, v2, v3
	v_add_u32_e32 v3, 0x25700, v51
	v_add3_u32 v2, s27, v76, v77
	ds_write_b128 v2, v[28:31]
	v_add_u32_e32 v2, 0x25500, v51
	global_load_dwordx4 v[56:59], v240, s[58:59] offset:1024
	ds_read_b128 v[28:31], v2
	ds_read_b128 v[32:35], v2 offset:16
	ds_read_b128 v[36:39], v3
	ds_read_b128 v[40:43], v3 offset:16
	s_nop 0
	v_lshlrev_b32_e32 v2, 16, v112
	v_and_b32_e32 v3, 0xffff0000, v112
	v_lshlrev_b32_e32 v44, 16, v116
	v_and_b32_e32 v45, 0xffff0000, v116
	v_lshlrev_b32_e32 v46, 16, v120
	v_and_b32_e32 v47, 0xffff0000, v120
	v_pk_add_f32 v[44:45], v[44:45], v[2:3] neg_lo:[0,1] neg_hi:[0,1]
	v_readlane_b32 s27, v253, 62
	s_waitcnt lgkmcnt(3)
	v_pk_fma_f32 v[28:29], v[44:45], v[28:29], v[2:3]
	v_pk_add_f32 v[2:3], v[46:47], v[2:3] neg_lo:[0,1] neg_hi:[0,1]
	v_lshlrev_b32_e32 v44, 16, v121
	s_waitcnt lgkmcnt(1)
	v_pk_fma_f32 v[2:3], v[2:3], v[36:37], v[28:29]
	v_lshlrev_b32_e32 v28, 16, v113
	v_and_b32_e32 v29, 0xffff0000, v113
	v_lshlrev_b32_e32 v36, 16, v117
	v_and_b32_e32 v37, 0xffff0000, v117
	v_and_b32_e32 v45, 0xffff0000, v121
	v_pk_add_f32 v[36:37], v[36:37], v[28:29] neg_lo:[0,1] neg_hi:[0,1]
	s_nop 0
	v_lshlrev_b32_e32 v46, 16, v144
	v_pk_fma_f32 v[30:31], v[36:37], v[30:31], v[28:29]
	v_pk_add_f32 v[28:29], v[44:45], v[28:29] neg_lo:[0,1] neg_hi:[0,1]
	v_lshlrev_b32_e32 v36, 16, v118
	v_pk_fma_f32 v[30:31], v[28:29], v[38:39], v[30:31]
	v_lshlrev_b32_e32 v28, 16, v114
	global_load_dwordx4 v[72:75], v240, s[54:55] offset:2048
	v_and_b32_e32 v29, 0xffff0000, v114
	v_and_b32_e32 v37, 0xffff0000, v118
	v_lshlrev_b32_e32 v38, 16, v122
	v_and_b32_e32 v39, 0xffff0000, v122
	v_pk_add_f32 v[36:37], v[36:37], v[28:29] neg_lo:[0,1] neg_hi:[0,1]
	v_lshlrev_b32_e32 v44, 16, v140
	v_pk_fma_f32 v[32:33], v[36:37], v[32:33], v[28:29]
	v_pk_add_f32 v[28:29], v[38:39], v[28:29] neg_lo:[0,1] neg_hi:[0,1]
	v_lshlrev_b32_e32 v36, 16, v119
	v_and_b32_e32 v37, 0xffff0000, v119
	v_lshlrev_b32_e32 v38, 16, v115
	v_and_b32_e32 v39, 0xffff0000, v115
	s_waitcnt lgkmcnt(0)
	v_pk_fma_f32 v[32:33], v[28:29], v[40:41], v[32:33]
	v_lshlrev_b32_e32 v28, 16, v123
	v_and_b32_e32 v29, 0xffff0000, v123
	v_pk_add_f32 v[36:37], v[36:37], v[38:39] neg_lo:[0,1] neg_hi:[0,1]
	v_pk_add_f32 v[28:29], v[28:29], v[38:39] neg_lo:[0,1] neg_hi:[0,1]
	v_pk_fma_f32 v[34:35], v[36:37], v[34:35], v[38:39]
	v_and_b32_e32 v45, 0xffff0000, v140
	v_pk_fma_f32 v[34:35], v[28:29], v[42:43], v[34:35]
	v_cvt_pk_bf16_f32 v28, v2, v3
	v_cvt_pk_bf16_f32 v29, v30, v31
	v_cvt_pk_bf16_f32 v30, v32, v33
	v_cvt_pk_bf16_f32 v31, v34, v35
	v_add3_u32 v2, s27, v76, v77
	ds_write_b128 v2, v[28:31]
	v_add_u32_e32 v2, 0x24e00, v51
	v_add_u32_e32 v3, 0x24f00, v51
	ds_read_b128 v[28:31], v2
	ds_read_b128 v[32:35], v2 offset:16
	ds_read_b128 v[36:39], v3
	ds_read_b128 v[40:43], v3 offset:16
	v_lshlrev_b32_e32 v2, 16, v136
	v_and_b32_e32 v3, 0xffff0000, v136
	v_and_b32_e32 v47, 0xffff0000, v144
	v_pk_add_f32 v[44:45], v[44:45], v[2:3] neg_lo:[0,1] neg_hi:[0,1]
	v_cmp_gt_i32_e32 vcc, 32, v1
	s_waitcnt lgkmcnt(3)
	v_pk_fma_f32 v[28:29], v[44:45], v[28:29], v[2:3]
	v_pk_add_f32 v[2:3], v[46:47], v[2:3] neg_lo:[0,1] neg_hi:[0,1]
	v_lshlrev_b32_e32 v44, 16, v145
	s_waitcnt lgkmcnt(1)
	v_pk_fma_f32 v[28:29], v[2:3], v[36:37], v[28:29]
	v_lshlrev_b32_e32 v2, 16, v137
	global_load_dwordx4 v[64:67], v240, s[58:59] offset:2048
	v_and_b32_e32 v3, 0xffff0000, v137
	v_lshlrev_b32_e32 v36, 16, v141
	v_and_b32_e32 v37, 0xffff0000, v141
	v_and_b32_e32 v45, 0xffff0000, v145
	v_pk_add_f32 v[36:37], v[36:37], v[2:3] neg_lo:[0,1] neg_hi:[0,1]
	v_lshlrev_b32_e32 v46, 16, v132
	v_pk_fma_f32 v[30:31], v[36:37], v[30:31], v[2:3]
	v_pk_add_f32 v[2:3], v[44:45], v[2:3] neg_lo:[0,1] neg_hi:[0,1]
	v_lshlrev_b32_e32 v36, 16, v142
	v_pk_fma_f32 v[30:31], v[2:3], v[38:39], v[30:31]
	v_lshlrev_b32_e32 v2, 16, v138
	v_and_b32_e32 v3, 0xffff0000, v138
	v_and_b32_e32 v37, 0xffff0000, v142
	v_lshlrev_b32_e32 v38, 16, v146
	v_and_b32_e32 v39, 0xffff0000, v146
	v_pk_add_f32 v[36:37], v[36:37], v[2:3] neg_lo:[0,1] neg_hi:[0,1]
	v_lshlrev_b32_e32 v44, 16, v128
	v_pk_fma_f32 v[32:33], v[36:37], v[32:33], v[2:3]
	v_pk_add_f32 v[2:3], v[38:39], v[2:3] neg_lo:[0,1] neg_hi:[0,1]
	v_lshlrev_b32_e32 v36, 16, v143
	v_and_b32_e32 v37, 0xffff0000, v143
	v_lshlrev_b32_e32 v38, 16, v139
	v_and_b32_e32 v39, 0xffff0000, v139
	s_waitcnt lgkmcnt(0)
	v_pk_fma_f32 v[32:33], v[2:3], v[40:41], v[32:33]
	v_lshlrev_b32_e32 v2, 16, v147
	v_and_b32_e32 v3, 0xffff0000, v147
	v_pk_add_f32 v[36:37], v[36:37], v[38:39] neg_lo:[0,1] neg_hi:[0,1]
	v_pk_add_f32 v[2:3], v[2:3], v[38:39] neg_lo:[0,1] neg_hi:[0,1]
	v_pk_fma_f32 v[34:35], v[36:37], v[34:35], v[38:39]
	v_and_b32_e32 v45, 0xffff0000, v128
	v_pk_fma_f32 v[34:35], v[2:3], v[42:43], v[34:35]
	v_mov_b32_e32 v2, 0x1d400
	v_mov_b32_e32 v3, 0xd800
	v_cndmask_b32_e32 v2, v2, v3, vcc
	v_lshlrev_b32_e32 v3, 8, v1
	v_add_u32_e32 v2, 0, v2
	v_and_b32_e32 v3, 0x1f00, v3
	v_add3_u32 v2, v2, v3, v50
	ds_write_b128 v2, v[28:31]
	ds_write_b128 v2, v[32:35] offset:16
	v_add_u32_e32 v2, 0x25000, v51
	v_add_u32_e32 v3, 0x25100, v51
	ds_read_b128 v[28:31], v2
	ds_read_b128 v[32:35], v2 offset:16
	global_load_dwordx4 v[68:71], v240, s[54:55] offset:3072
	ds_read_b128 v[36:39], v3
	ds_read_b128 v[40:43], v3 offset:16
	v_lshlrev_b32_e32 v2, 16, v124
	v_and_b32_e32 v3, 0xffff0000, v124
	v_and_b32_e32 v47, 0xffff0000, v132
	v_pk_add_f32 v[44:45], v[44:45], v[2:3] neg_lo:[0,1] neg_hi:[0,1]
	v_cmp_eq_u32_e32 vcc, 0, v49
	s_waitcnt lgkmcnt(3)
	v_pk_fma_f32 v[28:29], v[44:45], v[28:29], v[2:3]
	v_pk_add_f32 v[2:3], v[46:47], v[2:3] neg_lo:[0,1] neg_hi:[0,1]
	s_waitcnt lgkmcnt(1)
	v_pk_fma_f32 v[76:77], v[2:3], v[36:37], v[28:29]
	v_lshlrev_b32_e32 v2, 16, v125
	v_and_b32_e32 v3, 0xffff0000, v125
	v_lshlrev_b32_e32 v28, 16, v129
	v_and_b32_e32 v29, 0xffff0000, v129
	v_lshlrev_b32_e32 v36, 16, v133
	v_and_b32_e32 v37, 0xffff0000, v133
	v_pk_add_f32 v[28:29], v[28:29], v[2:3] neg_lo:[0,1] neg_hi:[0,1]
	s_nop 0
	v_pk_fma_f32 v[28:29], v[28:29], v[30:31], v[2:3]
	v_pk_add_f32 v[2:3], v[36:37], v[2:3] neg_lo:[0,1] neg_hi:[0,1]
	v_lshlrev_b32_e32 v30, 16, v134
	v_pk_fma_f32 v[78:79], v[2:3], v[38:39], v[28:29]
	v_lshlrev_b32_e32 v2, 16, v126
	v_and_b32_e32 v3, 0xffff0000, v126
	v_lshlrev_b32_e32 v28, 16, v130
	v_and_b32_e32 v29, 0xffff0000, v130
	v_and_b32_e32 v31, 0xffff0000, v134
	v_pk_add_f32 v[28:29], v[28:29], v[2:3] neg_lo:[0,1] neg_hi:[0,1]
	v_add_u32_e32 v38, 0x24700, v51
	v_pk_fma_f32 v[28:29], v[28:29], v[32:33], v[2:3]
	v_pk_add_f32 v[2:3], v[30:31], v[2:3] neg_lo:[0,1] neg_hi:[0,1]
	v_lshlrev_b32_e32 v32, 16, v127
	s_waitcnt lgkmcnt(0)
	v_pk_fma_f32 v[80:81], v[2:3], v[40:41], v[28:29]
	v_lshlrev_b32_e32 v28, 16, v131
	v_and_b32_e32 v29, 0xffff0000, v131
	v_and_b32_e32 v33, 0xffff0000, v127
	v_pk_add_f32 v[36:37], v[28:29], v[32:33] neg_lo:[0,1] neg_hi:[0,1]
	ds_read_b128 v[28:31], v38
	v_lshlrev_b32_e32 v2, 16, v135
	v_and_b32_e32 v3, 0xffff0000, v135
	v_pk_fma_f32 v[34:35], v[36:37], v[34:35], v[32:33]
	v_pk_add_f32 v[2:3], v[2:3], v[32:33] neg_lo:[0,1] neg_hi:[0,1]
	global_load_dwordx4 v[52:55], v240, s[58:59] offset:3072
	s_nop 0
	v_pk_fma_f32 v[82:83], v[2:3], v[42:43], v[34:35]
	ds_read_b128 v[32:35], v38 offset:16
	s_waitcnt lgkmcnt(1)
	v_mul_f32_e32 v3, v77, v29
	v_mul_f32_e32 v2, v76, v28
	v_mul_f32_e32 v3, v3, v3
	v_fmac_f32_e32 v3, v2, v2
	v_mul_f32_e32 v2, v78, v30
	v_fmac_f32_e32 v3, v2, v2
	v_mul_f32_e32 v2, v79, v31
	v_fmac_f32_e32 v3, v2, v2
	s_waitcnt lgkmcnt(0)
	v_mul_f32_e32 v2, v80, v32
	v_fmac_f32_e32 v3, v2, v2
	v_mul_f32_e32 v2, v81, v33
	v_fmac_f32_e32 v3, v2, v2
	v_mul_f32_e32 v2, v82, v34
	v_fmac_f32_e32 v3, v2, v2
	v_mul_f32_e32 v2, v83, v35
	v_lshlrev_b32_e32 v28, 2, v48
	v_fmac_f32_e32 v3, v2, v2
	s_nop 1
	v_add_f32_dpp v2, v3, v3 quad_perm:[1,0,3,2] row_mask:0xf bank_mask:0xf
	s_nop 1
	v_add_f32_dpp v2, v2, v2 quad_perm:[2,3,0,1] row_mask:0xf bank_mask:0xf
	s_nop 1
	v_mov_b32_dpp v3, v2 row_half_mirror row_mask:0xf bank_mask:0xf
	s_nop 1
	s_and_saveexec_b64 s[30:31], vcc
	s_cbranch_execz .LBB0_83
	s_waitcnt lgkmcnt(0)
	v_add_f32_e32 v2, v2, v3
	v_add_f32_e32 v2, 0x2b8cbccc, v2
	s_mov_b32 s27, 0xf800000
	v_mul_f32_e32 v3, 0x4f800000, v2
	v_cmp_gt_f32_e32 vcc, s27, v2
	v_lshl_add_u32 v1, v1, 2, 0
	v_add_u32_e32 v1, 0x24000, v1
	v_cndmask_b32_e32 v2, v2, v3, vcc
	v_sqrt_f32_e32 v3, v2
	s_nop 0
	v_add_u32_e32 v28, -1, v3
	v_fma_f32 v30, -v28, v3, v2
	v_add_u32_e32 v29, 1, v3
	v_cmp_ge_f32_e64 s[38:39], 0, v30
	s_nop 1
	v_cndmask_b32_e64 v28, v3, v28, s[38:39]
	v_fma_f32 v3, -v29, v3, v2
	v_cmp_lt_f32_e64 s[38:39], 0, v3
	s_nop 1
	v_cndmask_b32_e64 v3, v28, v29, s[38:39]
	v_mul_f32_e32 v28, 0x37800000, v3
	v_cndmask_b32_e32 v3, v3, v28, vcc
	v_cmp_class_f32_e32 vcc, v2, v222
	s_nop 1
	v_cndmask_b32_e32 v2, v3, v2, vcc
	v_div_scale_f32 v3, s[38:39], v2, v2, 1.0
	v_rcp_f32_e32 v28, v3
	s_nop 0
	v_fma_f32 v29, -v3, v28, 1.0
	v_fmac_f32_e32 v28, v29, v28
	v_div_scale_f32 v29, vcc, 1.0, v2, 1.0
	v_mul_f32_e32 v30, v29, v28
	v_fma_f32 v31, -v3, v30, v29
	v_fmac_f32_e32 v30, v31, v28
	v_fma_f32 v3, -v3, v30, v29
	v_div_fmas_f32 v3, v3, v28, v30
	v_div_fixup_f32 v2, v3, v2, 1.0
	ds_write_b32 v1, v2
